# v45 + GEMM phase-start prologue de-serialisation: both start-up LDS-DMA batches issued before the first wait (vmcnt(2)+barrier moved behind batch 2 as vmcnt(8))
# baseline (speedup 1.0000x reference)
; #define PG8_STAGE(bufoff, gbase, voff) do { _Pragma("unroll") for (int _i = 0; _i < 2; ++_i) \
;         __builtin_amdgcn_global_load_lds((const unsigned*)((const char*)(gbase) + (voff)[_i]), (PG8_LAS unsigned*)(lds + (bufoff) + ldsw + _i * 8192), 16, 0, 0); } while (0)
; #define PG8_WAIT_V(n) asm volatile("s_waitcnt vmcnt(" #n ")" ::: "memory")
; #define PG8_BAR __builtin_amdgcn_s_barrier()
; template <class Epi, class Sched, bool ALIGN_EPI = false, bool SP2 = false>
; __device__ __forceinline__ void gemm_phase(PG8_LAS unsigned char* lds, const Gemm g, const Sched& S, const Epi& E) {
;     ...
;     for (int i = 0; i < 2; ++i) { int R, C; stage_rc(tid * 16 + i * 8192, R, C); const int Rb = Epi::PERM ? ((R & ~31) + perm32(R & 31)) : R;
;         voffA[i] = (unsigned)(R * K + C) * 2u; voffB[i] = (unsigned)(Rb * K + C) * 2u; }
;     const size_t kstep = (size_t)(BK * 2);
;     const size_t hstep = (size_t)HALF * K * 2;
;     const size_t tstep = 2 * hstep;
;     const unsigned ldsw = (unsigned)wid * 1024u;
;     const int aoff = lds_byte(wr * 64 + fr, fq * 8), boff = lds_byte(wc * 32 + fr, fq * 8);
;     ...
;         PG8_STAGE(PG8_SB(0, 0), cB, voffB); PG8_STAGE(PG8_SB(0, 1), cB + hstep, voffB); PG8_STAGE(PG8_SA(0, 0), cA, voffA); PG8_STAGE(PG8_SA(0, 1), cA + hstep, voffA);
;         if (wr == 1) PG8_BAR;
;         PG8_WAIT_V(2); PG8_BAR;
;         PG8_STAGE(PG8_SB(1, 0), cB + kstep, voffB); PG8_STAGE(PG8_SA(1, 0), cA + kstep, voffA); PG8_STAGE(PG8_SB(1, 1), cB + hstep + kstep, voffB);
;         PG8_WAIT_V(6); PG8_BAR;
.LBB0_231:
	v_and_b32_e32 v143, 15, v14
	v_lshrrev_b32_e32 v14, 1, v14
	v_and_b32_e32 v14, 24, v14
	v_lshlrev_b32_e32 v15, 1, v14
	v_lshlrev_b32_e32 v16, 2, v143
	v_lshl_or_b32 v15, v143, 6, v15
	s_lshl_b32 s11, s10, 13
	v_and_b32_e32 v17, 32, v16
	v_bitop3_b32 v18, v15, s11, v17 bitop3:0xde
	s_lshl_b32 s11, s9, 5
	s_and_b32 s55, s11, 0x60
	s_lshr_b32 s53, s12, 6
	s_lshl_b32 s54, s10, 6
	s_lshl_b32 s9, s55, 7
	s_and_b64 s[12:13], s[94:95], exec
	s_cselect_b32 s57, 0x400, 0
	s_add_i32 m0, s49, 0x18000
	v_lshl_add_u64 v[6:7], v[6:7], 0, s[96:97]
	global_load_lds_dwordx4 v[6:7], off
	v_lshl_add_u64 v[4:5], v[4:5], 0, s[96:97]
	s_add_i32 m0, s49, 0x1a000
	s_add_i32 s58, s49, 0x8000
	s_add_i32 s59, s49, 0xa000
	global_load_lds_dwordx4 v[4:5], off
	v_lshl_add_u64 v[0:1], v[0:1], 0, s[96:97]
	s_mov_b32 m0, s58
	s_add_u32 s12, s44, 0x40080
	global_load_lds_dwordx4 v[0:1], off
	v_lshl_add_u64 v[0:1], v[2:3], 0, s[96:97]
	s_mov_b32 m0, s59
	s_addc_u32 s13, s45, 0
	global_load_lds_dwordx4 v[0:1], off
	s_add_i32 m0, s49, 0x1c000
	v_lshl_add_u64 v[0:1], s[12:13], 0, v[132:133]
	global_load_lds_dwordx4 v[0:1], off
	v_lshl_add_u64 v[0:1], s[12:13], 0, v[128:129]
	s_add_i32 m0, s49, 0x1e000
	v_and_b32_e32 v2, 1, v12
	global_load_lds_dwordx4 v[0:1], off
	s_waitcnt vmcnt(8)
	s_barrier
	v_lshlrev_b32_e32 v1, 14, v12
	v_and_b32_e32 v1, 0xffff8000, v1
	v_lshl_add_u32 v1, v11, 11, v1
	v_lshl_or_b32 v1, v2, 6, v1
	s_cmpk_lt_u32 s8, 0x100
	v_lshl_add_u32 v136, v13, 1, v1
	v_lshlrev_b32_e32 v1, 14, v8
	v_bitop3_b32 v145, v15, s9, v17 bitop3:0xde
	s_cselect_b64 s[8:9], -1, 0
	s_lshl_b32 s10, s10, 8
	v_and_b32_e32 v1, 0xffff8000, v1
	s_waitcnt vmcnt(6)
	s_add_i32 s10, s10, 0
	v_lshl_add_u32 v1, v9, 11, v1
	v_and_b32_e32 v2, 1, v8
	v_and_or_b32 v0, s11, 32, v14
	s_add_i32 s10, s10, 0x20000
	v_lshl_or_b32 v1, v2, 6, v1
	s_mov_b32 s56, 0
	v_add_u32_e32 v147, s10, v16
	v_mov_b32_e32 v137, v157
	v_lshl_add_u32 v138, v10, 1, v1
	v_mov_b32_e32 v139, v157
	v_add_u32_e32 v149, 0, v18
	v_lshlrev_b32_e32 v140, 1, v0
	s_barrier
	s_waitcnt vmcnt(0)
	s_branch .LBB0_234

; #define PG8_STAGE(bufoff, gbase, voff) do { _Pragma("unroll") for (int _i = 0; _i < 2; ++_i) \
;         __builtin_amdgcn_global_load_lds((const unsigned*)((const char*)(gbase) + (voff)[_i]), (PG8_LAS unsigned*)(lds + (bufoff) + ldsw + _i * 8192), 16, 0, 0); } while (0)
; #define PG8_WAIT_V(n) asm volatile("s_waitcnt vmcnt(" #n ")" ::: "memory")
; #define PG8_BAR __builtin_amdgcn_s_barrier()
; template <class Epi, class Sched, bool ALIGN_EPI = false, bool SP2 = false>
; __device__ __forceinline__ void gemm_phase(PG8_LAS unsigned char* lds, const Gemm g, const Sched& S, const Epi& E) {
;     ...
;     for (int i = 0; i < 2; ++i) { int R, C; stage_rc(tid * 16 + i * 8192, R, C); const int Rb = Epi::PERM ? ((R & ~31) + perm32(R & 31)) : R;
;         voffA[i] = (unsigned)(R * K + C) * 2u; voffB[i] = (unsigned)(Rb * K + C) * 2u; }
;     const size_t kstep = (size_t)(BK * 2);
;     const size_t hstep = (size_t)HALF * K * 2;
;     const size_t tstep = 2 * hstep;
;     const unsigned ldsw = (unsigned)wid * 1024u;
;     const int aoff = lds_byte(wr * 64 + fr, fq * 8), boff = lds_byte(wc * 32 + fr, fq * 8);
;     ...
;         PG8_STAGE(PG8_SB(0, 0), cB, voffB); PG8_STAGE(PG8_SB(0, 1), cB + hstep, voffB); PG8_STAGE(PG8_SA(0, 0), cA, voffA); PG8_STAGE(PG8_SA(0, 1), cA + hstep, voffA);
;         if (wr == 1) PG8_BAR;
;         PG8_WAIT_V(2); PG8_BAR;
;         PG8_STAGE(PG8_SB(1, 0), cB + kstep, voffB); PG8_STAGE(PG8_SA(1, 0), cA + kstep, voffA); PG8_STAGE(PG8_SB(1, 1), cB + hstep + kstep, voffB);
;         PG8_WAIT_V(6); PG8_BAR;
; __global__ void __launch_bounds__(NTHR, 2) fwd_megakernel(Args a) {
;     ...
;                 for (int rep = 0; rep < RPT_DOWN; ++rep) { pg8::EpiRes E{XB, XL, part, (ph == NPHASES - 1 && rep == RPT_DOWN - 1) ? outp : nullptr, rep == RPT_DOWN - 1 ? 0.5f : 0.0f};
.LBB0_250:
	s_cmp_eq_u32 s80, 28
	s_cselect_b32 s47, s77, 0
	s_cselect_b32 s46, s76, 0
	v_bfe_u32 v13, v12, 4, 2
	s_cmp_eq_u64 s[46:47], 0
	v_and_b32_e32 v12, 15, v12
	v_lshlrev_b32_e32 v19, 4, v13
	v_readlane_b32 s14, v254, 23
	s_cselect_b64 s[48:49], -1, 0
	s_cmp_lg_u64 s[46:47], 0
	v_lshl_or_b32 v158, s7, 6, v12
	v_lshl_or_b32 v19, v12, 6, v19
	v_lshlrev_b32_e32 v12, 2, v12
	v_mov_b32_e32 v175, v157
	v_readlane_b32 s15, v254, 24
	s_cselect_b64 s[50:51], -1, 0
	s_and_b32 s10, s8, 3
	s_lshl_b32 s7, s7, 13
	v_and_b32_e32 v20, 32, v12
	s_add_i32 m0, s21, 0x18000
	v_lshl_add_u64 v[0:1], v[0:1], 0, s[96:97]
	v_lshl_add_u64 v[14:15], s[14:15], 0, v[174:175]
	v_mov_b32_e32 v173, v157
	v_bitop3_b32 v21, v19, s7, v20 bitop3:0xde
	s_lshl_b32 s7, s10, 12
	global_load_lds_dwordx4 v[0:1], off
	v_lshl_add_u64 v[0:1], v[2:3], 0, s[96:97]
	s_add_i32 m0, s21, 0x1a000
	s_add_i32 s57, s21, 0x8000
	s_add_i32 s58, s21, 0xa000
	v_lshl_add_u64 v[16:17], s[14:15], 0, v[172:173]
	global_load_lds_dwordx4 v[0:1], off
	v_lshl_add_u64 v[0:1], v[14:15], 0, s[96:97]
	s_mov_b32 m0, s57
	s_add_u32 s8, s12, 0xb0080
	global_load_lds_dwordx4 v[0:1], off
	v_lshl_add_u64 v[0:1], v[16:17], 0, s[96:97]
	s_mov_b32 m0, s58
	s_addc_u32 s9, s13, 0
	global_load_lds_dwordx4 v[0:1], off
	s_add_i32 m0, s21, 0x1c000
	v_lshl_add_u64 v[0:1], s[8:9], 0, v[156:157]
	global_load_lds_dwordx4 v[0:1], off
	v_lshl_add_u64 v[0:1], s[8:9], 0, v[170:171]
	s_add_i32 m0, s21, 0x1e000
	s_cmpk_lt_u32 s6, 0x100
	global_load_lds_dwordx4 v[0:1], off
	s_waitcnt vmcnt(8)
	s_barrier
	v_lshlrev_b32_e32 v0, 6, v13
	s_movk_i32 s6, 0x80
	s_movk_i32 s8, 0xb00
	s_cselect_b64 s[52:53], -1, 0
	v_bitop3_b32 v237, v0, 64, v12 bitop3:0x36
	v_bitop3_b32 v238, v0, s6, v12 bitop3:0x36
	s_lshl_b32 s6, s10, 2
	v_lshrrev_b32_e32 v1, 1, v9
	v_mul_lo_u32 v0, v8, s8
	s_mov_b32 s9, 0xb000
	v_bitop3_b32 v169, v19, s7, v20 bitop3:0xde
	s_add_u32 s59, s68, s6
	v_mad_u64_u32 v[0:1], s[6:7], v1, s9, v[0:1]
	v_lshlrev_b32_e32 v18, 3, v13
	v_or_b32_e32 v0, v0, v10
	v_lshl_or_b32 v236, s10, 5, v18
	v_add_lshl_u32 v0, v0, v11, 1
	v_mov_b32_e32 v1, v157
	s_mov_b64 s[10:11], 0xb0080
	v_lshl_add_u64 v[176:177], v[0:1], 0, s[10:11]
	v_lshrrev_b32_e32 v1, 1, v4
	v_mul_lo_u32 v0, v5, s8
	v_mad_u64_u32 v[0:1], s[6:7], v1, s9, v[0:1]
	s_waitcnt vmcnt(6)
	v_or_b32_e32 v0, v0, v6
	v_add_lshl_u32 v0, v0, v7, 1
	v_mov_b32_e32 v1, v157
	v_readlane_b32 s6, v254, 21
	s_mov_b32 s56, 0
	v_cmp_eq_u32_e64 s[40:41], 0, v13
	s_addc_u32 s60, s69, 0
	v_lshl_add_u64 v[178:179], v[0:1], 0, s[10:11]
	v_add_u32_e32 v239, 0, v21
	v_readlane_b32 s61, v254, 6
	s_mov_b32 s28, s6
	s_mov_b64 s[10:11], s[14:15]
	s_barrier
	v_readlane_b32 s7, v254, 22
	s_branch .LBB0_253

; #define PG8_STAGE(bufoff, gbase, voff) do { _Pragma("unroll") for (int _i = 0; _i < 2; ++_i) \
;         __builtin_amdgcn_global_load_lds((const unsigned*)((const char*)(gbase) + (voff)[_i]), (PG8_LAS unsigned*)(lds + (bufoff) + ldsw + _i * 8192), 16, 0, 0); } while (0)
; #define PG8_WAIT_V(n) asm volatile("s_waitcnt vmcnt(" #n ")" ::: "memory")
; #define PG8_BAR __builtin_amdgcn_s_barrier()
; template <class Epi, class Sched, bool ALIGN_EPI = false, bool SP2 = false>
; __device__ __forceinline__ void gemm_phase(PG8_LAS unsigned char* lds, const Gemm g, const Sched& S, const Epi& E) {
;     ...
;     for (int i = 0; i < 2; ++i) { int R, C; stage_rc(tid * 16 + i * 8192, R, C); const int Rb = Epi::PERM ? ((R & ~31) + perm32(R & 31)) : R;
;         voffA[i] = (unsigned)(R * K + C) * 2u; voffB[i] = (unsigned)(Rb * K + C) * 2u; }
;     const size_t kstep = (size_t)(BK * 2);
;     const size_t hstep = (size_t)HALF * K * 2;
;     const size_t tstep = 2 * hstep;
;     const unsigned ldsw = (unsigned)wid * 1024u;
;     const int aoff = lds_byte(wr * 64 + fr, fq * 8), boff = lds_byte(wc * 32 + fr, fq * 8);
;     ...
;         PG8_STAGE(PG8_SB(0, 0), cB, voffB); PG8_STAGE(PG8_SB(0, 1), cB + hstep, voffB); PG8_STAGE(PG8_SA(0, 0), cA, voffA); PG8_STAGE(PG8_SA(0, 1), cA + hstep, voffA);
;         if (wr == 1) PG8_BAR;
;         PG8_WAIT_V(2); PG8_BAR;
;         PG8_STAGE(PG8_SB(1, 0), cB + kstep, voffB); PG8_STAGE(PG8_SA(1, 0), cA + kstep, voffA); PG8_STAGE(PG8_SB(1, 1), cB + hstep + kstep, voffB);
;         PG8_WAIT_V(6); PG8_BAR;
.LBB0_346:
	v_bfe_u32 v11, v10, 4, 2
	v_and_b32_e32 v10, 15, v10
	v_lshlrev_b32_e32 v17, 4, v11
	v_readlane_b32 s30, v254, 17
	v_lshl_or_b32 v158, s7, 6, v10
	v_lshl_or_b32 v17, v10, 6, v17
	v_lshlrev_b32_e32 v10, 2, v10
	v_mov_b32_e32 v175, v157
	v_readlane_b32 s31, v254, 18
	s_and_b32 s27, s10, 3
	s_lshl_b32 s7, s7, 13
	v_and_b32_e32 v18, 32, v10
	s_add_i32 m0, s15, 0x18000
	v_lshl_add_u64 v[0:1], v[0:1], 0, s[96:97]
	v_lshl_add_u64 v[12:13], s[30:31], 0, v[174:175]
	v_mov_b32_e32 v173, v157
	v_bitop3_b32 v19, v17, s7, v18 bitop3:0xde
	s_lshl_b32 s7, s27, 12
	global_load_lds_dwordx4 v[0:1], off
	v_lshl_add_u64 v[0:1], v[2:3], 0, s[96:97]
	s_add_i32 m0, s15, 0x1a000
	s_add_i32 s19, s15, 0x8000
	s_add_i32 s20, s15, 0xa000
	v_lshl_add_u64 v[14:15], s[30:31], 0, v[172:173]
	global_load_lds_dwordx4 v[0:1], off
	v_lshl_add_u64 v[0:1], v[12:13], 0, s[96:97]
	s_mov_b32 m0, s19
	s_add_u32 s10, s8, 0x40080
	global_load_lds_dwordx4 v[0:1], off
	v_lshl_add_u64 v[0:1], v[14:15], 0, s[96:97]
	s_mov_b32 m0, s20
	s_addc_u32 s11, s9, 0
	global_load_lds_dwordx4 v[0:1], off
	s_add_i32 m0, s15, 0x1c000
	v_lshl_add_u64 v[0:1], s[10:11], 0, v[156:157]
	global_load_lds_dwordx4 v[0:1], off
	v_lshl_add_u64 v[0:1], s[10:11], 0, v[170:171]
	s_add_i32 m0, s15, 0x1e000
	s_cmpk_lt_u32 s6, 0x100
	global_load_lds_dwordx4 v[0:1], off
	s_waitcnt vmcnt(8)
	s_barrier
	v_lshlrev_b32_e32 v0, 6, v11
	s_movk_i32 s6, 0x80
	v_bitop3_b32 v237, v0, 64, v10 bitop3:0x36
	v_bitop3_b32 v238, v0, s6, v10 bitop3:0x36
	v_lshlrev_b32_e32 v0, 14, v8
	v_and_b32_e32 v0, 0xffff8000, v0
	v_lshl_add_u32 v0, v7, 11, v0
	v_and_b32_e32 v1, 1, v8
	v_lshl_or_b32 v0, v1, 6, v0
	v_lshl_add_u32 v176, v9, 1, v0
	v_lshlrev_b32_e32 v0, 14, v4
	v_lshlrev_b32_e32 v16, 3, v11
	s_cselect_b64 s[42:43], -1, 0
	s_lshl_b32 s6, s27, 2
	v_and_b32_e32 v0, 0xffff8000, v0
	v_bitop3_b32 v169, v17, s7, v18 bitop3:0xde
	s_waitcnt vmcnt(6)
	v_lshl_or_b32 v236, s27, 5, v16
	s_add_u32 s27, s68, s6
	v_lshl_add_u32 v0, v5, 11, v0
	v_and_b32_e32 v1, 1, v4
	v_readlane_b32 s6, v254, 21
	v_lshl_or_b32 v0, v1, 6, v0
	v_readlane_b32 s7, v254, 22
	s_mov_b32 s21, 0
	v_cmp_eq_u32_e64 s[38:39], 0, v11
	s_addc_u32 s52, s69, 0
	v_mov_b32_e32 v177, v157
	v_lshl_add_u32 v178, v6, 1, v0
	v_mov_b32_e32 v179, v157
	v_add_u32_e32 v239, 0, v19
	v_readlane_b32 s53, v254, 6
	s_mov_b32 s28, s6
	s_mov_b64 s[6:7], s[30:31]
	s_barrier
	s_branch .LBB0_349

; #define PG8_STAGE(bufoff, gbase, voff) do { _Pragma("unroll") for (int _i = 0; _i < 2; ++_i) \
;         __builtin_amdgcn_global_load_lds((const unsigned*)((const char*)(gbase) + (voff)[_i]), (PG8_LAS unsigned*)(lds + (bufoff) + ldsw + _i * 8192), 16, 0, 0); } while (0)
; #define PG8_WAIT_V(n) asm volatile("s_waitcnt vmcnt(" #n ")" ::: "memory")
; #define PG8_BAR __builtin_amdgcn_s_barrier()
; template <class Epi, class Sched, bool ALIGN_EPI = false, bool SP2 = false>
; __device__ __forceinline__ void gemm_phase(PG8_LAS unsigned char* lds, const Gemm g, const Sched& S, const Epi& E) {
;     ...
;     for (int i = 0; i < 2; ++i) { int R, C; stage_rc(tid * 16 + i * 8192, R, C); const int Rb = Epi::PERM ? ((R & ~31) + perm32(R & 31)) : R;
;         voffA[i] = (unsigned)(R * K + C) * 2u; voffB[i] = (unsigned)(Rb * K + C) * 2u; }
;     const size_t kstep = (size_t)(BK * 2);
;     const size_t hstep = (size_t)HALF * K * 2;
;     const size_t tstep = 2 * hstep;
;     const unsigned ldsw = (unsigned)wid * 1024u;
;     const int aoff = lds_byte(wr * 64 + fr, fq * 8), boff = lds_byte(wc * 32 + fr, fq * 8);
;     ...
;         PG8_STAGE(PG8_SB(0, 0), cB, voffB); PG8_STAGE(PG8_SB(0, 1), cB + hstep, voffB); PG8_STAGE(PG8_SA(0, 0), cA, voffA); PG8_STAGE(PG8_SA(0, 1), cA + hstep, voffA);
;         if (wr == 1) PG8_BAR;
;         PG8_WAIT_V(2); PG8_BAR;
;         PG8_STAGE(PG8_SB(1, 0), cB + kstep, voffB); PG8_STAGE(PG8_SA(1, 0), cA + kstep, voffA); PG8_STAGE(PG8_SB(1, 1), cB + hstep + kstep, voffB);
;         PG8_WAIT_V(6); PG8_BAR;
.LBB0_393:
	v_readlane_b32 s38, v254, 9
	s_lshl_b32 s7, s7, 5
	v_mov_b32_e32 v133, v157
	v_readlane_b32 s39, v254, 10
	s_and_b32 s14, s7, 0x60
	s_add_i32 m0, s25, 0x18000
	v_lshl_add_u64 v[0:1], v[0:1], 0, s[96:97]
	v_lshl_add_u64 v[12:13], s[38:39], 0, v[132:133]
	v_mov_b32_e32 v131, v157
	s_lshl_b32 s9, s8, 13
	s_lshl_b32 s7, s14, 7
	global_load_lds_dwordx4 v[0:1], off
	v_lshl_add_u64 v[0:1], v[2:3], 0, s[96:97]
	s_add_i32 m0, s25, 0x1a000
	s_add_i32 s29, s25, 0x8000
	s_add_i32 s30, s25, 0xa000
	v_lshl_add_u64 v[14:15], s[38:39], 0, v[130:131]
	global_load_lds_dwordx4 v[0:1], off
	v_lshl_add_u64 v[0:1], v[12:13], 0, s[96:97]
	s_mov_b32 m0, s29
	s_add_u32 s10, s12, 0x40080
	global_load_lds_dwordx4 v[0:1], off
	v_lshl_add_u64 v[0:1], v[14:15], 0, s[96:97]
	s_mov_b32 m0, s30
	s_addc_u32 s11, s13, 0
	global_load_lds_dwordx4 v[0:1], off
	s_add_i32 m0, s25, 0x1c000
	v_lshl_add_u64 v[0:1], s[10:11], 0, v[156:157]
	global_load_lds_dwordx4 v[0:1], off
	v_lshl_add_u64 v[0:1], s[10:11], 0, v[128:129]
	s_add_i32 m0, s25, 0x1e000
	s_cmpk_lt_u32 s6, 0x100
	global_load_lds_dwordx4 v[0:1], off
	s_waitcnt vmcnt(8)
	s_barrier
	v_lshrrev_b32_e32 v1, 1, v4
	v_and_b32_e32 v1, 24, v1
	v_and_b32_e32 v0, 15, v4
	v_lshlrev_b32_e32 v2, 1, v1
	v_lshl_or_b32 v148, s8, 6, v0
	v_lshl_or_b32 v2, v0, 6, v2
	v_lshlrev_b32_e32 v0, 2, v0
	v_and_b32_e32 v3, 32, v0
	v_bitop3_b32 v149, v2, s7, v3 bitop3:0xde
	s_cselect_b64 s[6:7], -1, 0
	s_lshl_b32 s8, s8, 8
	s_add_i32 s8, s8, 0
	s_add_i32 s8, s8, 0x20000
	v_add_u32_e32 v150, s8, v0
	v_lshlrev_b32_e32 v0, 14, v9
	v_and_b32_e32 v0, 0xffff8000, v0
	v_or_b32_e32 v151, s14, v1
	v_lshl_add_u32 v0, v8, 11, v0
	v_and_b32_e32 v1, 1, v9
	v_lshl_or_b32 v0, v1, 6, v0
	v_lshl_add_u32 v134, v10, 1, v0
	v_lshlrev_b32_e32 v0, 14, v5
	v_and_b32_e32 v0, 0xffff8000, v0
	s_waitcnt vmcnt(6)
	v_lshl_add_u32 v0, v6, 11, v0
	v_and_b32_e32 v1, 1, v5
	v_bitop3_b32 v4, v2, s9, v3 bitop3:0xde
	v_lshl_or_b32 v0, v1, 6, v0
	v_readlane_b32 s8, v254, 7
	v_mov_b32_e32 v135, v157
	v_lshl_add_u32 v136, v7, 1, v0
	v_mov_b32_e32 v137, v157
	s_mov_b32 s31, 0
	v_add_u32_e32 v152, 0, v4
	v_readlane_b32 s34, v254, 3
	s_mov_b32 s35, s8
	s_mov_b64 s[10:11], s[38:39]
	s_barrier
	v_readlane_b32 s9, v254, 8
	s_branch .LBB0_396
